# peerq top-16 scan: 64 LDS score reads prefetched before the insertion network (fully unrolled, same med3/max sequence)
# speedup vs baseline: 1.0061x; 1.0029x over previous
.LBB0_42:
	v_add_u32_e32 v0, 0x400, v154
	ds_write2_b32 v154, v50, v34 offset1:32
	ds_write2_b32 v154, v51, v35 offset0:129 offset1:161
	ds_write2_b32 v0, v52, v36 offset0:2 offset1:34
	ds_write2_b32 v0, v53, v37 offset0:131 offset1:163
	v_add_u32_e32 v0, 0x1000, v154
	ds_write2_b32 v0, v54, v38 offset0:8 offset1:40
	ds_write2_b32 v0, v55, v39 offset0:137 offset1:169
	v_add_u32_e32 v0, 0x1400, v154
	ds_write2_b32 v0, v56, v40 offset0:10 offset1:42
	ds_write2_b32 v0, v57, v41 offset0:139 offset1:171
	v_add_u32_e32 v0, 0x2000, v154
	ds_write2_b32 v0, v58, v42 offset0:16 offset1:48
	ds_write2_b32 v0, v59, v43 offset0:145 offset1:177
	v_add_u32_e32 v0, 0x2400, v154
	ds_write2_b32 v0, v60, v44 offset0:18 offset1:50
	ds_write2_b32 v0, v61, v45 offset0:147 offset1:179
	v_add_u32_e32 v0, 0x3000, v154
	ds_write2_b32 v0, v62, v46 offset0:24 offset1:56
	ds_write2_b32 v0, v63, v47 offset0:153 offset1:185
	v_add_u32_e32 v0, 0x3400, v154
	ds_write2_b32 v0, v64, v48 offset0:26 offset1:58
	ds_write2_b32 v0, v65, v49 offset0:155 offset1:187
	v_add_u32_e32 v0, 0x4000, v154
	ds_write2_b32 v0, v18, v2 offset0:32 offset1:64
	ds_write2_b32 v0, v19, v3 offset0:161 offset1:193
	v_add_u32_e32 v0, 0x4400, v154
	ds_write2_b32 v0, v20, v4 offset0:34 offset1:66
	ds_write2_b32 v0, v21, v5 offset0:163 offset1:195
	v_add_u32_e32 v0, 0x5000, v154
	ds_write2_b32 v0, v22, v6 offset0:40 offset1:72
	ds_write2_b32 v0, v23, v7 offset0:169 offset1:201
	v_add_u32_e32 v0, 0x5400, v154
	ds_write2_b32 v0, v24, v8 offset0:42 offset1:74
	ds_write2_b32 v0, v25, v9 offset0:171 offset1:203
	v_add_u32_e32 v0, 0x6000, v154
	ds_write2_b32 v0, v26, v10 offset0:48 offset1:80
	ds_write2_b32 v0, v27, v11 offset0:177 offset1:209
	v_add_u32_e32 v0, 0x6400, v154
	ds_write2_b32 v0, v28, v12 offset0:50 offset1:82
	ds_write2_b32 v0, v29, v13 offset0:179 offset1:211
	v_add_u32_e32 v0, 0x7000, v154
	ds_write2_b32 v0, v30, v14 offset0:56 offset1:88
	ds_write2_b32 v0, v31, v15 offset0:185 offset1:217
	v_add_u32_e32 v0, 0x7400, v154
	ds_write2_b32 v0, v32, v16 offset0:58 offset1:90
	ds_write2_b32 v0, v33, v17 offset0:187 offset1:219
	v_mov_b32_e32 v2, 0xff800000
	s_mov_b32 s4, 0
	v_mov_b32_e32 v0, v156
	v_mov_b32_e32 v3, 0xff800000
	v_mov_b32_e32 v4, 0xff800000
	v_mov_b32_e32 v5, 0xff800000
	v_mov_b32_e32 v6, 0xff800000
	v_mov_b32_e32 v7, 0xff800000
	v_mov_b32_e32 v8, 0xff800000
	v_mov_b32_e32 v9, 0xff800000
	v_mov_b32_e32 v10, 0xff800000
	v_mov_b32_e32 v11, 0xff800000
	v_mov_b32_e32 v12, 0xff800000
	v_mov_b32_e32 v13, 0xff800000
	v_mov_b32_e32 v14, 0xff800000
	v_mov_b32_e32 v15, 0xff800000
	v_mov_b32_e32 v16, 0xff800000
	v_mov_b32_e32 v17, 0xff800000
	s_waitcnt lgkmcnt(0)
	s_barrier
	ds_read2_b32 v[98:99], v156 offset1:1
	ds_read2_b32 v[100:101], v156 offset0:2 offset1:3
	ds_read2_b32 v[102:103], v156 offset0:4 offset1:5
	ds_read2_b32 v[104:105], v156 offset0:6 offset1:7
	ds_read2_b32 v[106:107], v156 offset0:8 offset1:9
	ds_read2_b32 v[108:109], v156 offset0:10 offset1:11
	ds_read2_b32 v[110:111], v156 offset0:12 offset1:13
	ds_read2_b32 v[112:113], v156 offset0:14 offset1:15
	ds_read2_b32 v[114:115], v156 offset0:16 offset1:17
	ds_read2_b32 v[116:117], v156 offset0:18 offset1:19
	ds_read2_b32 v[118:119], v156 offset0:20 offset1:21
	ds_read2_b32 v[120:121], v156 offset0:22 offset1:23
	ds_read2_b32 v[122:123], v156 offset0:24 offset1:25
	ds_read2_b32 v[124:125], v156 offset0:26 offset1:27
	ds_read2_b32 v[126:127], v156 offset0:28 offset1:29
	ds_read2_b32 v[128:129], v156 offset0:30 offset1:31
	ds_read2_b32 v[162:163], v156 offset0:32 offset1:33
	ds_read2_b32 v[164:165], v156 offset0:34 offset1:35
	ds_read2_b32 v[166:167], v156 offset0:36 offset1:37
	ds_read2_b32 v[168:169], v156 offset0:38 offset1:39
	ds_read2_b32 v[170:171], v156 offset0:40 offset1:41
	ds_read2_b32 v[172:173], v156 offset0:42 offset1:43
	ds_read2_b32 v[174:175], v156 offset0:44 offset1:45
	ds_read2_b32 v[176:177], v156 offset0:46 offset1:47
	ds_read2_b32 v[178:179], v156 offset0:48 offset1:49
	ds_read2_b32 v[180:181], v156 offset0:50 offset1:51
	ds_read2_b32 v[182:183], v156 offset0:52 offset1:53
	ds_read2_b32 v[184:185], v156 offset0:54 offset1:55
	ds_read2_b32 v[186:187], v156 offset0:56 offset1:57
	ds_read2_b32 v[188:189], v156 offset0:58 offset1:59
	ds_read2_b32 v[190:191], v156 offset0:60 offset1:61
	ds_read2_b32 v[192:193], v156 offset0:62 offset1:63
	s_waitcnt lgkmcnt(15)
	v_and_b32_e32 v98, 0xffffff80, v98
	v_or3_b32 v98, v155, v98, 0
	v_med3_f32 v17, v98, v16, v17
	v_med3_f32 v16, v98, v15, v16
	v_med3_f32 v15, v98, v14, v15
	v_med3_f32 v14, v98, v13, v14
	v_med3_f32 v13, v98, v12, v13
	v_med3_f32 v12, v98, v11, v12
	v_med3_f32 v11, v98, v10, v11
	v_med3_f32 v10, v98, v9, v10
	v_med3_f32 v9, v98, v8, v9
	v_med3_f32 v8, v98, v7, v8
	v_med3_f32 v7, v98, v6, v7
	v_med3_f32 v6, v98, v5, v6
	v_med3_f32 v5, v98, v4, v5
	v_med3_f32 v4, v98, v3, v4
	v_med3_f32 v3, v98, v2, v3
	v_max_f32_e32 v2, v98, v2
	v_and_b32_e32 v99, 0xffffff80, v99
	v_or3_b32 v99, v155, v99, 1
	v_med3_f32 v17, v99, v16, v17
	v_med3_f32 v16, v99, v15, v16
	v_med3_f32 v15, v99, v14, v15
	v_med3_f32 v14, v99, v13, v14
	v_med3_f32 v13, v99, v12, v13
	v_med3_f32 v12, v99, v11, v12
	v_med3_f32 v11, v99, v10, v11
	v_med3_f32 v10, v99, v9, v10
	v_med3_f32 v9, v99, v8, v9
	v_med3_f32 v8, v99, v7, v8
	v_med3_f32 v7, v99, v6, v7
	v_med3_f32 v6, v99, v5, v6
	v_med3_f32 v5, v99, v4, v5
	v_med3_f32 v4, v99, v3, v4
	v_med3_f32 v3, v99, v2, v3
	v_max_f32_e32 v2, v99, v2
	s_waitcnt lgkmcnt(15)
	v_and_b32_e32 v100, 0xffffff80, v100
	v_or3_b32 v100, v155, v100, 2
	v_med3_f32 v17, v100, v16, v17
	v_med3_f32 v16, v100, v15, v16
	v_med3_f32 v15, v100, v14, v15
	v_med3_f32 v14, v100, v13, v14
	v_med3_f32 v13, v100, v12, v13
	v_med3_f32 v12, v100, v11, v12
	v_med3_f32 v11, v100, v10, v11
	v_med3_f32 v10, v100, v9, v10
	v_med3_f32 v9, v100, v8, v9
	v_med3_f32 v8, v100, v7, v8
	v_med3_f32 v7, v100, v6, v7
	v_med3_f32 v6, v100, v5, v6
	v_med3_f32 v5, v100, v4, v5
	v_med3_f32 v4, v100, v3, v4
	v_med3_f32 v3, v100, v2, v3
	v_max_f32_e32 v2, v100, v2
	v_and_b32_e32 v101, 0xffffff80, v101
	v_or3_b32 v101, v155, v101, 3
	v_med3_f32 v17, v101, v16, v17
	v_med3_f32 v16, v101, v15, v16
	v_med3_f32 v15, v101, v14, v15
	v_med3_f32 v14, v101, v13, v14
	v_med3_f32 v13, v101, v12, v13
	v_med3_f32 v12, v101, v11, v12
	v_med3_f32 v11, v101, v10, v11
	v_med3_f32 v10, v101, v9, v10
	v_med3_f32 v9, v101, v8, v9
	v_med3_f32 v8, v101, v7, v8
	v_med3_f32 v7, v101, v6, v7
	v_med3_f32 v6, v101, v5, v6
	v_med3_f32 v5, v101, v4, v5
	v_med3_f32 v4, v101, v3, v4
	v_med3_f32 v3, v101, v2, v3
	v_max_f32_e32 v2, v101, v2
	s_waitcnt lgkmcnt(15)
	v_and_b32_e32 v102, 0xffffff80, v102
	v_or3_b32 v102, v155, v102, 4
	v_med3_f32 v17, v102, v16, v17
	v_med3_f32 v16, v102, v15, v16
	v_med3_f32 v15, v102, v14, v15
	v_med3_f32 v14, v102, v13, v14
	v_med3_f32 v13, v102, v12, v13
	v_med3_f32 v12, v102, v11, v12
	v_med3_f32 v11, v102, v10, v11
	v_med3_f32 v10, v102, v9, v10
	v_med3_f32 v9, v102, v8, v9
	v_med3_f32 v8, v102, v7, v8
	v_med3_f32 v7, v102, v6, v7
	v_med3_f32 v6, v102, v5, v6
	v_med3_f32 v5, v102, v4, v5
	v_med3_f32 v4, v102, v3, v4
	v_med3_f32 v3, v102, v2, v3
	v_max_f32_e32 v2, v102, v2
	v_and_b32_e32 v103, 0xffffff80, v103
	v_or3_b32 v103, v155, v103, 5
	v_med3_f32 v17, v103, v16, v17
	v_med3_f32 v16, v103, v15, v16
	v_med3_f32 v15, v103, v14, v15
	v_med3_f32 v14, v103, v13, v14
	v_med3_f32 v13, v103, v12, v13
	v_med3_f32 v12, v103, v11, v12
	v_med3_f32 v11, v103, v10, v11
	v_med3_f32 v10, v103, v9, v10
	v_med3_f32 v9, v103, v8, v9
	v_med3_f32 v8, v103, v7, v8
	v_med3_f32 v7, v103, v6, v7
	v_med3_f32 v6, v103, v5, v6
	v_med3_f32 v5, v103, v4, v5
	v_med3_f32 v4, v103, v3, v4
	v_med3_f32 v3, v103, v2, v3
	v_max_f32_e32 v2, v103, v2
	s_waitcnt lgkmcnt(15)
	v_and_b32_e32 v104, 0xffffff80, v104
	v_or3_b32 v104, v155, v104, 6
	v_med3_f32 v17, v104, v16, v17
	v_med3_f32 v16, v104, v15, v16
	v_med3_f32 v15, v104, v14, v15
	v_med3_f32 v14, v104, v13, v14
	v_med3_f32 v13, v104, v12, v13
	v_med3_f32 v12, v104, v11, v12
	v_med3_f32 v11, v104, v10, v11
	v_med3_f32 v10, v104, v9, v10
	v_med3_f32 v9, v104, v8, v9
	v_med3_f32 v8, v104, v7, v8
	v_med3_f32 v7, v104, v6, v7
	v_med3_f32 v6, v104, v5, v6
	v_med3_f32 v5, v104, v4, v5
	v_med3_f32 v4, v104, v3, v4
	v_med3_f32 v3, v104, v2, v3
	v_max_f32_e32 v2, v104, v2
	v_and_b32_e32 v105, 0xffffff80, v105
	v_or3_b32 v105, v155, v105, 7
	v_med3_f32 v17, v105, v16, v17
	v_med3_f32 v16, v105, v15, v16
	v_med3_f32 v15, v105, v14, v15
	v_med3_f32 v14, v105, v13, v14
	v_med3_f32 v13, v105, v12, v13
	v_med3_f32 v12, v105, v11, v12
	v_med3_f32 v11, v105, v10, v11
	v_med3_f32 v10, v105, v9, v10
	v_med3_f32 v9, v105, v8, v9
	v_med3_f32 v8, v105, v7, v8
	v_med3_f32 v7, v105, v6, v7
	v_med3_f32 v6, v105, v5, v6
	v_med3_f32 v5, v105, v4, v5
	v_med3_f32 v4, v105, v3, v4
	v_med3_f32 v3, v105, v2, v3
	v_max_f32_e32 v2, v105, v2
	s_waitcnt lgkmcnt(15)
	v_and_b32_e32 v106, 0xffffff80, v106
	v_or3_b32 v106, v155, v106, 8
	v_med3_f32 v17, v106, v16, v17
	v_med3_f32 v16, v106, v15, v16
	v_med3_f32 v15, v106, v14, v15
	v_med3_f32 v14, v106, v13, v14
	v_med3_f32 v13, v106, v12, v13
	v_med3_f32 v12, v106, v11, v12
	v_med3_f32 v11, v106, v10, v11
	v_med3_f32 v10, v106, v9, v10
	v_med3_f32 v9, v106, v8, v9
	v_med3_f32 v8, v106, v7, v8
	v_med3_f32 v7, v106, v6, v7
	v_med3_f32 v6, v106, v5, v6
	v_med3_f32 v5, v106, v4, v5
	v_med3_f32 v4, v106, v3, v4
	v_med3_f32 v3, v106, v2, v3
	v_max_f32_e32 v2, v106, v2
	v_and_b32_e32 v107, 0xffffff80, v107
	v_or3_b32 v107, v155, v107, 9
	v_med3_f32 v17, v107, v16, v17
	v_med3_f32 v16, v107, v15, v16
	v_med3_f32 v15, v107, v14, v15
	v_med3_f32 v14, v107, v13, v14
	v_med3_f32 v13, v107, v12, v13
	v_med3_f32 v12, v107, v11, v12
	v_med3_f32 v11, v107, v10, v11
	v_med3_f32 v10, v107, v9, v10
	v_med3_f32 v9, v107, v8, v9
	v_med3_f32 v8, v107, v7, v8
	v_med3_f32 v7, v107, v6, v7
	v_med3_f32 v6, v107, v5, v6
	v_med3_f32 v5, v107, v4, v5
	v_med3_f32 v4, v107, v3, v4
	v_med3_f32 v3, v107, v2, v3
	v_max_f32_e32 v2, v107, v2
	s_waitcnt lgkmcnt(15)
	v_and_b32_e32 v108, 0xffffff80, v108
	v_or3_b32 v108, v155, v108, 10
	v_med3_f32 v17, v108, v16, v17
	v_med3_f32 v16, v108, v15, v16
	v_med3_f32 v15, v108, v14, v15
	v_med3_f32 v14, v108, v13, v14
	v_med3_f32 v13, v108, v12, v13
	v_med3_f32 v12, v108, v11, v12
	v_med3_f32 v11, v108, v10, v11
	v_med3_f32 v10, v108, v9, v10
	v_med3_f32 v9, v108, v8, v9
	v_med3_f32 v8, v108, v7, v8
	v_med3_f32 v7, v108, v6, v7
	v_med3_f32 v6, v108, v5, v6
	v_med3_f32 v5, v108, v4, v5
	v_med3_f32 v4, v108, v3, v4
	v_med3_f32 v3, v108, v2, v3
	v_max_f32_e32 v2, v108, v2
	v_and_b32_e32 v109, 0xffffff80, v109
	v_or3_b32 v109, v155, v109, 11
	v_med3_f32 v17, v109, v16, v17
	v_med3_f32 v16, v109, v15, v16
	v_med3_f32 v15, v109, v14, v15
	v_med3_f32 v14, v109, v13, v14
	v_med3_f32 v13, v109, v12, v13
	v_med3_f32 v12, v109, v11, v12
	v_med3_f32 v11, v109, v10, v11
	v_med3_f32 v10, v109, v9, v10
	v_med3_f32 v9, v109, v8, v9
	v_med3_f32 v8, v109, v7, v8
	v_med3_f32 v7, v109, v6, v7
	v_med3_f32 v6, v109, v5, v6
	v_med3_f32 v5, v109, v4, v5
	v_med3_f32 v4, v109, v3, v4
	v_med3_f32 v3, v109, v2, v3
	v_max_f32_e32 v2, v109, v2
	s_waitcnt lgkmcnt(15)
	v_and_b32_e32 v110, 0xffffff80, v110
	v_or3_b32 v110, v155, v110, 12
	v_med3_f32 v17, v110, v16, v17
	v_med3_f32 v16, v110, v15, v16
	v_med3_f32 v15, v110, v14, v15
	v_med3_f32 v14, v110, v13, v14
	v_med3_f32 v13, v110, v12, v13
	v_med3_f32 v12, v110, v11, v12
	v_med3_f32 v11, v110, v10, v11
	v_med3_f32 v10, v110, v9, v10
	v_med3_f32 v9, v110, v8, v9
	v_med3_f32 v8, v110, v7, v8
	v_med3_f32 v7, v110, v6, v7
	v_med3_f32 v6, v110, v5, v6
	v_med3_f32 v5, v110, v4, v5
	v_med3_f32 v4, v110, v3, v4
	v_med3_f32 v3, v110, v2, v3
	v_max_f32_e32 v2, v110, v2
	v_and_b32_e32 v111, 0xffffff80, v111
	v_or3_b32 v111, v155, v111, 13
	v_med3_f32 v17, v111, v16, v17
	v_med3_f32 v16, v111, v15, v16
	v_med3_f32 v15, v111, v14, v15
	v_med3_f32 v14, v111, v13, v14
	v_med3_f32 v13, v111, v12, v13
	v_med3_f32 v12, v111, v11, v12
	v_med3_f32 v11, v111, v10, v11
	v_med3_f32 v10, v111, v9, v10
	v_med3_f32 v9, v111, v8, v9
	v_med3_f32 v8, v111, v7, v8
	v_med3_f32 v7, v111, v6, v7
	v_med3_f32 v6, v111, v5, v6
	v_med3_f32 v5, v111, v4, v5
	v_med3_f32 v4, v111, v3, v4
	v_med3_f32 v3, v111, v2, v3
	v_max_f32_e32 v2, v111, v2
	s_waitcnt lgkmcnt(15)
	v_and_b32_e32 v112, 0xffffff80, v112
	v_or3_b32 v112, v155, v112, 14
	v_med3_f32 v17, v112, v16, v17
	v_med3_f32 v16, v112, v15, v16
	v_med3_f32 v15, v112, v14, v15
	v_med3_f32 v14, v112, v13, v14
	v_med3_f32 v13, v112, v12, v13
	v_med3_f32 v12, v112, v11, v12
	v_med3_f32 v11, v112, v10, v11
	v_med3_f32 v10, v112, v9, v10
	v_med3_f32 v9, v112, v8, v9
	v_med3_f32 v8, v112, v7, v8
	v_med3_f32 v7, v112, v6, v7
	v_med3_f32 v6, v112, v5, v6
	v_med3_f32 v5, v112, v4, v5
	v_med3_f32 v4, v112, v3, v4
	v_med3_f32 v3, v112, v2, v3
	v_max_f32_e32 v2, v112, v2
	v_and_b32_e32 v113, 0xffffff80, v113
	v_or3_b32 v113, v155, v113, 15
	v_med3_f32 v17, v113, v16, v17
	v_med3_f32 v16, v113, v15, v16
	v_med3_f32 v15, v113, v14, v15
	v_med3_f32 v14, v113, v13, v14
	v_med3_f32 v13, v113, v12, v13
	v_med3_f32 v12, v113, v11, v12
	v_med3_f32 v11, v113, v10, v11
	v_med3_f32 v10, v113, v9, v10
	v_med3_f32 v9, v113, v8, v9
	v_med3_f32 v8, v113, v7, v8
	v_med3_f32 v7, v113, v6, v7
	v_med3_f32 v6, v113, v5, v6
	v_med3_f32 v5, v113, v4, v5
	v_med3_f32 v4, v113, v3, v4
	v_med3_f32 v3, v113, v2, v3
	v_max_f32_e32 v2, v113, v2
	s_waitcnt lgkmcnt(15)
	v_and_b32_e32 v114, 0xffffff80, v114
	v_or3_b32 v114, v155, v114, 16
	v_med3_f32 v17, v114, v16, v17
	v_med3_f32 v16, v114, v15, v16
	v_med3_f32 v15, v114, v14, v15
	v_med3_f32 v14, v114, v13, v14
	v_med3_f32 v13, v114, v12, v13
	v_med3_f32 v12, v114, v11, v12
	v_med3_f32 v11, v114, v10, v11
	v_med3_f32 v10, v114, v9, v10
	v_med3_f32 v9, v114, v8, v9
	v_med3_f32 v8, v114, v7, v8
	v_med3_f32 v7, v114, v6, v7
	v_med3_f32 v6, v114, v5, v6
	v_med3_f32 v5, v114, v4, v5
	v_med3_f32 v4, v114, v3, v4
	v_med3_f32 v3, v114, v2, v3
	v_max_f32_e32 v2, v114, v2
	v_and_b32_e32 v115, 0xffffff80, v115
	v_or3_b32 v115, v155, v115, 17
	v_med3_f32 v17, v115, v16, v17
	v_med3_f32 v16, v115, v15, v16
	v_med3_f32 v15, v115, v14, v15
	v_med3_f32 v14, v115, v13, v14
	v_med3_f32 v13, v115, v12, v13
	v_med3_f32 v12, v115, v11, v12
	v_med3_f32 v11, v115, v10, v11
	v_med3_f32 v10, v115, v9, v10
	v_med3_f32 v9, v115, v8, v9
	v_med3_f32 v8, v115, v7, v8
	v_med3_f32 v7, v115, v6, v7
	v_med3_f32 v6, v115, v5, v6
	v_med3_f32 v5, v115, v4, v5
	v_med3_f32 v4, v115, v3, v4
	v_med3_f32 v3, v115, v2, v3
	v_max_f32_e32 v2, v115, v2
	s_waitcnt lgkmcnt(15)
	v_and_b32_e32 v116, 0xffffff80, v116
	v_or3_b32 v116, v155, v116, 18
	v_med3_f32 v17, v116, v16, v17
	v_med3_f32 v16, v116, v15, v16
	v_med3_f32 v15, v116, v14, v15
	v_med3_f32 v14, v116, v13, v14
	v_med3_f32 v13, v116, v12, v13
	v_med3_f32 v12, v116, v11, v12
	v_med3_f32 v11, v116, v10, v11
	v_med3_f32 v10, v116, v9, v10
	v_med3_f32 v9, v116, v8, v9
	v_med3_f32 v8, v116, v7, v8
	v_med3_f32 v7, v116, v6, v7
	v_med3_f32 v6, v116, v5, v6
	v_med3_f32 v5, v116, v4, v5
	v_med3_f32 v4, v116, v3, v4
	v_med3_f32 v3, v116, v2, v3
	v_max_f32_e32 v2, v116, v2
	v_and_b32_e32 v117, 0xffffff80, v117
	v_or3_b32 v117, v155, v117, 19
	v_med3_f32 v17, v117, v16, v17
	v_med3_f32 v16, v117, v15, v16
	v_med3_f32 v15, v117, v14, v15
	v_med3_f32 v14, v117, v13, v14
	v_med3_f32 v13, v117, v12, v13
	v_med3_f32 v12, v117, v11, v12
	v_med3_f32 v11, v117, v10, v11
	v_med3_f32 v10, v117, v9, v10
	v_med3_f32 v9, v117, v8, v9
	v_med3_f32 v8, v117, v7, v8
	v_med3_f32 v7, v117, v6, v7
	v_med3_f32 v6, v117, v5, v6
	v_med3_f32 v5, v117, v4, v5
	v_med3_f32 v4, v117, v3, v4
	v_med3_f32 v3, v117, v2, v3
	v_max_f32_e32 v2, v117, v2
	s_waitcnt lgkmcnt(15)
	v_and_b32_e32 v118, 0xffffff80, v118
	v_or3_b32 v118, v155, v118, 20
	v_med3_f32 v17, v118, v16, v17
	v_med3_f32 v16, v118, v15, v16
	v_med3_f32 v15, v118, v14, v15
	v_med3_f32 v14, v118, v13, v14
	v_med3_f32 v13, v118, v12, v13
	v_med3_f32 v12, v118, v11, v12
	v_med3_f32 v11, v118, v10, v11
	v_med3_f32 v10, v118, v9, v10
	v_med3_f32 v9, v118, v8, v9
	v_med3_f32 v8, v118, v7, v8
	v_med3_f32 v7, v118, v6, v7
	v_med3_f32 v6, v118, v5, v6
	v_med3_f32 v5, v118, v4, v5
	v_med3_f32 v4, v118, v3, v4
	v_med3_f32 v3, v118, v2, v3
	v_max_f32_e32 v2, v118, v2
	v_and_b32_e32 v119, 0xffffff80, v119
	v_or3_b32 v119, v155, v119, 21
	v_med3_f32 v17, v119, v16, v17
	v_med3_f32 v16, v119, v15, v16
	v_med3_f32 v15, v119, v14, v15
	v_med3_f32 v14, v119, v13, v14
	v_med3_f32 v13, v119, v12, v13
	v_med3_f32 v12, v119, v11, v12
	v_med3_f32 v11, v119, v10, v11
	v_med3_f32 v10, v119, v9, v10
	v_med3_f32 v9, v119, v8, v9
	v_med3_f32 v8, v119, v7, v8
	v_med3_f32 v7, v119, v6, v7
	v_med3_f32 v6, v119, v5, v6
	v_med3_f32 v5, v119, v4, v5
	v_med3_f32 v4, v119, v3, v4
	v_med3_f32 v3, v119, v2, v3
	v_max_f32_e32 v2, v119, v2
	s_waitcnt lgkmcnt(15)
	v_and_b32_e32 v120, 0xffffff80, v120
	v_or3_b32 v120, v155, v120, 22
	v_med3_f32 v17, v120, v16, v17
	v_med3_f32 v16, v120, v15, v16
	v_med3_f32 v15, v120, v14, v15
	v_med3_f32 v14, v120, v13, v14
	v_med3_f32 v13, v120, v12, v13
	v_med3_f32 v12, v120, v11, v12
	v_med3_f32 v11, v120, v10, v11
	v_med3_f32 v10, v120, v9, v10
	v_med3_f32 v9, v120, v8, v9
	v_med3_f32 v8, v120, v7, v8
	v_med3_f32 v7, v120, v6, v7
	v_med3_f32 v6, v120, v5, v6
	v_med3_f32 v5, v120, v4, v5
	v_med3_f32 v4, v120, v3, v4
	v_med3_f32 v3, v120, v2, v3
	v_max_f32_e32 v2, v120, v2
	v_and_b32_e32 v121, 0xffffff80, v121
	v_or3_b32 v121, v155, v121, 23
	v_med3_f32 v17, v121, v16, v17
	v_med3_f32 v16, v121, v15, v16
	v_med3_f32 v15, v121, v14, v15
	v_med3_f32 v14, v121, v13, v14
	v_med3_f32 v13, v121, v12, v13
	v_med3_f32 v12, v121, v11, v12
	v_med3_f32 v11, v121, v10, v11
	v_med3_f32 v10, v121, v9, v10
	v_med3_f32 v9, v121, v8, v9
	v_med3_f32 v8, v121, v7, v8
	v_med3_f32 v7, v121, v6, v7
	v_med3_f32 v6, v121, v5, v6
	v_med3_f32 v5, v121, v4, v5
	v_med3_f32 v4, v121, v3, v4
	v_med3_f32 v3, v121, v2, v3
	v_max_f32_e32 v2, v121, v2
	s_waitcnt lgkmcnt(15)
	v_and_b32_e32 v122, 0xffffff80, v122
	v_or3_b32 v122, v155, v122, 24
	v_med3_f32 v17, v122, v16, v17
	v_med3_f32 v16, v122, v15, v16
	v_med3_f32 v15, v122, v14, v15
	v_med3_f32 v14, v122, v13, v14
	v_med3_f32 v13, v122, v12, v13
	v_med3_f32 v12, v122, v11, v12
	v_med3_f32 v11, v122, v10, v11
	v_med3_f32 v10, v122, v9, v10
	v_med3_f32 v9, v122, v8, v9
	v_med3_f32 v8, v122, v7, v8
	v_med3_f32 v7, v122, v6, v7
	v_med3_f32 v6, v122, v5, v6
	v_med3_f32 v5, v122, v4, v5
	v_med3_f32 v4, v122, v3, v4
	v_med3_f32 v3, v122, v2, v3
	v_max_f32_e32 v2, v122, v2
	v_and_b32_e32 v123, 0xffffff80, v123
	v_or3_b32 v123, v155, v123, 25
	v_med3_f32 v17, v123, v16, v17
	v_med3_f32 v16, v123, v15, v16
	v_med3_f32 v15, v123, v14, v15
	v_med3_f32 v14, v123, v13, v14
	v_med3_f32 v13, v123, v12, v13
	v_med3_f32 v12, v123, v11, v12
	v_med3_f32 v11, v123, v10, v11
	v_med3_f32 v10, v123, v9, v10
	v_med3_f32 v9, v123, v8, v9
	v_med3_f32 v8, v123, v7, v8
	v_med3_f32 v7, v123, v6, v7
	v_med3_f32 v6, v123, v5, v6
	v_med3_f32 v5, v123, v4, v5
	v_med3_f32 v4, v123, v3, v4
	v_med3_f32 v3, v123, v2, v3
	v_max_f32_e32 v2, v123, v2
	s_waitcnt lgkmcnt(15)
	v_and_b32_e32 v124, 0xffffff80, v124
	v_or3_b32 v124, v155, v124, 26
	v_med3_f32 v17, v124, v16, v17
	v_med3_f32 v16, v124, v15, v16
	v_med3_f32 v15, v124, v14, v15
	v_med3_f32 v14, v124, v13, v14
	v_med3_f32 v13, v124, v12, v13
	v_med3_f32 v12, v124, v11, v12
	v_med3_f32 v11, v124, v10, v11
	v_med3_f32 v10, v124, v9, v10
	v_med3_f32 v9, v124, v8, v9
	v_med3_f32 v8, v124, v7, v8
	v_med3_f32 v7, v124, v6, v7
	v_med3_f32 v6, v124, v5, v6
	v_med3_f32 v5, v124, v4, v5
	v_med3_f32 v4, v124, v3, v4
	v_med3_f32 v3, v124, v2, v3
	v_max_f32_e32 v2, v124, v2
	v_and_b32_e32 v125, 0xffffff80, v125
	v_or3_b32 v125, v155, v125, 27
	v_med3_f32 v17, v125, v16, v17
	v_med3_f32 v16, v125, v15, v16
	v_med3_f32 v15, v125, v14, v15
	v_med3_f32 v14, v125, v13, v14
	v_med3_f32 v13, v125, v12, v13
	v_med3_f32 v12, v125, v11, v12
	v_med3_f32 v11, v125, v10, v11
	v_med3_f32 v10, v125, v9, v10
	v_med3_f32 v9, v125, v8, v9
	v_med3_f32 v8, v125, v7, v8
	v_med3_f32 v7, v125, v6, v7
	v_med3_f32 v6, v125, v5, v6
	v_med3_f32 v5, v125, v4, v5
	v_med3_f32 v4, v125, v3, v4
	v_med3_f32 v3, v125, v2, v3
	v_max_f32_e32 v2, v125, v2
	s_waitcnt lgkmcnt(15)
	v_and_b32_e32 v126, 0xffffff80, v126
	v_or3_b32 v126, v155, v126, 28
	v_med3_f32 v17, v126, v16, v17
	v_med3_f32 v16, v126, v15, v16
	v_med3_f32 v15, v126, v14, v15
	v_med3_f32 v14, v126, v13, v14
	v_med3_f32 v13, v126, v12, v13
	v_med3_f32 v12, v126, v11, v12
	v_med3_f32 v11, v126, v10, v11
	v_med3_f32 v10, v126, v9, v10
	v_med3_f32 v9, v126, v8, v9
	v_med3_f32 v8, v126, v7, v8
	v_med3_f32 v7, v126, v6, v7
	v_med3_f32 v6, v126, v5, v6
	v_med3_f32 v5, v126, v4, v5
	v_med3_f32 v4, v126, v3, v4
	v_med3_f32 v3, v126, v2, v3
	v_max_f32_e32 v2, v126, v2
	v_and_b32_e32 v127, 0xffffff80, v127
	v_or3_b32 v127, v155, v127, 29
	v_med3_f32 v17, v127, v16, v17
	v_med3_f32 v16, v127, v15, v16
	v_med3_f32 v15, v127, v14, v15
	v_med3_f32 v14, v127, v13, v14
	v_med3_f32 v13, v127, v12, v13
	v_med3_f32 v12, v127, v11, v12
	v_med3_f32 v11, v127, v10, v11
	v_med3_f32 v10, v127, v9, v10
	v_med3_f32 v9, v127, v8, v9
	v_med3_f32 v8, v127, v7, v8
	v_med3_f32 v7, v127, v6, v7
	v_med3_f32 v6, v127, v5, v6
	v_med3_f32 v5, v127, v4, v5
	v_med3_f32 v4, v127, v3, v4
	v_med3_f32 v3, v127, v2, v3
	v_max_f32_e32 v2, v127, v2
	s_waitcnt lgkmcnt(15)
	v_and_b32_e32 v128, 0xffffff80, v128
	v_or3_b32 v128, v155, v128, 30
	v_med3_f32 v17, v128, v16, v17
	v_med3_f32 v16, v128, v15, v16
	v_med3_f32 v15, v128, v14, v15
	v_med3_f32 v14, v128, v13, v14
	v_med3_f32 v13, v128, v12, v13
	v_med3_f32 v12, v128, v11, v12
	v_med3_f32 v11, v128, v10, v11
	v_med3_f32 v10, v128, v9, v10
	v_med3_f32 v9, v128, v8, v9
	v_med3_f32 v8, v128, v7, v8
	v_med3_f32 v7, v128, v6, v7
	v_med3_f32 v6, v128, v5, v6
	v_med3_f32 v5, v128, v4, v5
	v_med3_f32 v4, v128, v3, v4
	v_med3_f32 v3, v128, v2, v3
	v_max_f32_e32 v2, v128, v2
	v_and_b32_e32 v129, 0xffffff80, v129
	v_or3_b32 v129, v155, v129, 31
	v_med3_f32 v17, v129, v16, v17
	v_med3_f32 v16, v129, v15, v16
	v_med3_f32 v15, v129, v14, v15
	v_med3_f32 v14, v129, v13, v14
	v_med3_f32 v13, v129, v12, v13
	v_med3_f32 v12, v129, v11, v12
	v_med3_f32 v11, v129, v10, v11
	v_med3_f32 v10, v129, v9, v10
	v_med3_f32 v9, v129, v8, v9
	v_med3_f32 v8, v129, v7, v8
	v_med3_f32 v7, v129, v6, v7
	v_med3_f32 v6, v129, v5, v6
	v_med3_f32 v5, v129, v4, v5
	v_med3_f32 v4, v129, v3, v4
	v_med3_f32 v3, v129, v2, v3
	v_max_f32_e32 v2, v129, v2
	s_waitcnt lgkmcnt(15)
	v_and_b32_e32 v162, 0xffffff80, v162
	v_or3_b32 v162, v155, v162, 32
	v_med3_f32 v17, v162, v16, v17
	v_med3_f32 v16, v162, v15, v16
	v_med3_f32 v15, v162, v14, v15
	v_med3_f32 v14, v162, v13, v14
	v_med3_f32 v13, v162, v12, v13
	v_med3_f32 v12, v162, v11, v12
	v_med3_f32 v11, v162, v10, v11
	v_med3_f32 v10, v162, v9, v10
	v_med3_f32 v9, v162, v8, v9
	v_med3_f32 v8, v162, v7, v8
	v_med3_f32 v7, v162, v6, v7
	v_med3_f32 v6, v162, v5, v6
	v_med3_f32 v5, v162, v4, v5
	v_med3_f32 v4, v162, v3, v4
	v_med3_f32 v3, v162, v2, v3
	v_max_f32_e32 v2, v162, v2
	v_and_b32_e32 v163, 0xffffff80, v163
	v_or3_b32 v163, v155, v163, 33
	v_med3_f32 v17, v163, v16, v17
	v_med3_f32 v16, v163, v15, v16
	v_med3_f32 v15, v163, v14, v15
	v_med3_f32 v14, v163, v13, v14
	v_med3_f32 v13, v163, v12, v13
	v_med3_f32 v12, v163, v11, v12
	v_med3_f32 v11, v163, v10, v11
	v_med3_f32 v10, v163, v9, v10
	v_med3_f32 v9, v163, v8, v9
	v_med3_f32 v8, v163, v7, v8
	v_med3_f32 v7, v163, v6, v7
	v_med3_f32 v6, v163, v5, v6
	v_med3_f32 v5, v163, v4, v5
	v_med3_f32 v4, v163, v3, v4
	v_med3_f32 v3, v163, v2, v3
	v_max_f32_e32 v2, v163, v2
	s_waitcnt lgkmcnt(14)
	v_and_b32_e32 v164, 0xffffff80, v164
	v_or3_b32 v164, v155, v164, 34
	v_med3_f32 v17, v164, v16, v17
	v_med3_f32 v16, v164, v15, v16
	v_med3_f32 v15, v164, v14, v15
	v_med3_f32 v14, v164, v13, v14
	v_med3_f32 v13, v164, v12, v13
	v_med3_f32 v12, v164, v11, v12
	v_med3_f32 v11, v164, v10, v11
	v_med3_f32 v10, v164, v9, v10
	v_med3_f32 v9, v164, v8, v9
	v_med3_f32 v8, v164, v7, v8
	v_med3_f32 v7, v164, v6, v7
	v_med3_f32 v6, v164, v5, v6
	v_med3_f32 v5, v164, v4, v5
	v_med3_f32 v4, v164, v3, v4
	v_med3_f32 v3, v164, v2, v3
	v_max_f32_e32 v2, v164, v2
	v_and_b32_e32 v165, 0xffffff80, v165
	v_or3_b32 v165, v155, v165, 35
	v_med3_f32 v17, v165, v16, v17
	v_med3_f32 v16, v165, v15, v16
	v_med3_f32 v15, v165, v14, v15
	v_med3_f32 v14, v165, v13, v14
	v_med3_f32 v13, v165, v12, v13
	v_med3_f32 v12, v165, v11, v12
	v_med3_f32 v11, v165, v10, v11
	v_med3_f32 v10, v165, v9, v10
	v_med3_f32 v9, v165, v8, v9
	v_med3_f32 v8, v165, v7, v8
	v_med3_f32 v7, v165, v6, v7
	v_med3_f32 v6, v165, v5, v6
	v_med3_f32 v5, v165, v4, v5
	v_med3_f32 v4, v165, v3, v4
	v_med3_f32 v3, v165, v2, v3
	v_max_f32_e32 v2, v165, v2
	s_waitcnt lgkmcnt(13)
	v_and_b32_e32 v166, 0xffffff80, v166
	v_or3_b32 v166, v155, v166, 36
	v_med3_f32 v17, v166, v16, v17
	v_med3_f32 v16, v166, v15, v16
	v_med3_f32 v15, v166, v14, v15
	v_med3_f32 v14, v166, v13, v14
	v_med3_f32 v13, v166, v12, v13
	v_med3_f32 v12, v166, v11, v12
	v_med3_f32 v11, v166, v10, v11
	v_med3_f32 v10, v166, v9, v10
	v_med3_f32 v9, v166, v8, v9
	v_med3_f32 v8, v166, v7, v8
	v_med3_f32 v7, v166, v6, v7
	v_med3_f32 v6, v166, v5, v6
	v_med3_f32 v5, v166, v4, v5
	v_med3_f32 v4, v166, v3, v4
	v_med3_f32 v3, v166, v2, v3
	v_max_f32_e32 v2, v166, v2
	v_and_b32_e32 v167, 0xffffff80, v167
	v_or3_b32 v167, v155, v167, 37
	v_med3_f32 v17, v167, v16, v17
	v_med3_f32 v16, v167, v15, v16
	v_med3_f32 v15, v167, v14, v15
	v_med3_f32 v14, v167, v13, v14
	v_med3_f32 v13, v167, v12, v13
	v_med3_f32 v12, v167, v11, v12
	v_med3_f32 v11, v167, v10, v11
	v_med3_f32 v10, v167, v9, v10
	v_med3_f32 v9, v167, v8, v9
	v_med3_f32 v8, v167, v7, v8
	v_med3_f32 v7, v167, v6, v7
	v_med3_f32 v6, v167, v5, v6
	v_med3_f32 v5, v167, v4, v5
	v_med3_f32 v4, v167, v3, v4
	v_med3_f32 v3, v167, v2, v3
	v_max_f32_e32 v2, v167, v2
	s_waitcnt lgkmcnt(12)
	v_and_b32_e32 v168, 0xffffff80, v168
	v_or3_b32 v168, v155, v168, 38
	v_med3_f32 v17, v168, v16, v17
	v_med3_f32 v16, v168, v15, v16
	v_med3_f32 v15, v168, v14, v15
	v_med3_f32 v14, v168, v13, v14
	v_med3_f32 v13, v168, v12, v13
	v_med3_f32 v12, v168, v11, v12
	v_med3_f32 v11, v168, v10, v11
	v_med3_f32 v10, v168, v9, v10
	v_med3_f32 v9, v168, v8, v9
	v_med3_f32 v8, v168, v7, v8
	v_med3_f32 v7, v168, v6, v7
	v_med3_f32 v6, v168, v5, v6
	v_med3_f32 v5, v168, v4, v5
	v_med3_f32 v4, v168, v3, v4
	v_med3_f32 v3, v168, v2, v3
	v_max_f32_e32 v2, v168, v2
	v_and_b32_e32 v169, 0xffffff80, v169
	v_or3_b32 v169, v155, v169, 39
	v_med3_f32 v17, v169, v16, v17
	v_med3_f32 v16, v169, v15, v16
	v_med3_f32 v15, v169, v14, v15
	v_med3_f32 v14, v169, v13, v14
	v_med3_f32 v13, v169, v12, v13
	v_med3_f32 v12, v169, v11, v12
	v_med3_f32 v11, v169, v10, v11
	v_med3_f32 v10, v169, v9, v10
	v_med3_f32 v9, v169, v8, v9
	v_med3_f32 v8, v169, v7, v8
	v_med3_f32 v7, v169, v6, v7
	v_med3_f32 v6, v169, v5, v6
	v_med3_f32 v5, v169, v4, v5
	v_med3_f32 v4, v169, v3, v4
	v_med3_f32 v3, v169, v2, v3
	v_max_f32_e32 v2, v169, v2
	s_waitcnt lgkmcnt(11)
	v_and_b32_e32 v170, 0xffffff80, v170
	v_or3_b32 v170, v155, v170, 40
	v_med3_f32 v17, v170, v16, v17
	v_med3_f32 v16, v170, v15, v16
	v_med3_f32 v15, v170, v14, v15
	v_med3_f32 v14, v170, v13, v14
	v_med3_f32 v13, v170, v12, v13
	v_med3_f32 v12, v170, v11, v12
	v_med3_f32 v11, v170, v10, v11
	v_med3_f32 v10, v170, v9, v10
	v_med3_f32 v9, v170, v8, v9
	v_med3_f32 v8, v170, v7, v8
	v_med3_f32 v7, v170, v6, v7
	v_med3_f32 v6, v170, v5, v6
	v_med3_f32 v5, v170, v4, v5
	v_med3_f32 v4, v170, v3, v4
	v_med3_f32 v3, v170, v2, v3
	v_max_f32_e32 v2, v170, v2
	v_and_b32_e32 v171, 0xffffff80, v171
	v_or3_b32 v171, v155, v171, 41
	v_med3_f32 v17, v171, v16, v17
	v_med3_f32 v16, v171, v15, v16
	v_med3_f32 v15, v171, v14, v15
	v_med3_f32 v14, v171, v13, v14
	v_med3_f32 v13, v171, v12, v13
	v_med3_f32 v12, v171, v11, v12
	v_med3_f32 v11, v171, v10, v11
	v_med3_f32 v10, v171, v9, v10
	v_med3_f32 v9, v171, v8, v9
	v_med3_f32 v8, v171, v7, v8
	v_med3_f32 v7, v171, v6, v7
	v_med3_f32 v6, v171, v5, v6
	v_med3_f32 v5, v171, v4, v5
	v_med3_f32 v4, v171, v3, v4
	v_med3_f32 v3, v171, v2, v3
	v_max_f32_e32 v2, v171, v2
	s_waitcnt lgkmcnt(10)
	v_and_b32_e32 v172, 0xffffff80, v172
	v_or3_b32 v172, v155, v172, 42
	v_med3_f32 v17, v172, v16, v17
	v_med3_f32 v16, v172, v15, v16
	v_med3_f32 v15, v172, v14, v15
	v_med3_f32 v14, v172, v13, v14
	v_med3_f32 v13, v172, v12, v13
	v_med3_f32 v12, v172, v11, v12
	v_med3_f32 v11, v172, v10, v11
	v_med3_f32 v10, v172, v9, v10
	v_med3_f32 v9, v172, v8, v9
	v_med3_f32 v8, v172, v7, v8
	v_med3_f32 v7, v172, v6, v7
	v_med3_f32 v6, v172, v5, v6
	v_med3_f32 v5, v172, v4, v5
	v_med3_f32 v4, v172, v3, v4
	v_med3_f32 v3, v172, v2, v3
	v_max_f32_e32 v2, v172, v2
	v_and_b32_e32 v173, 0xffffff80, v173
	v_or3_b32 v173, v155, v173, 43
	v_med3_f32 v17, v173, v16, v17
	v_med3_f32 v16, v173, v15, v16
	v_med3_f32 v15, v173, v14, v15
	v_med3_f32 v14, v173, v13, v14
	v_med3_f32 v13, v173, v12, v13
	v_med3_f32 v12, v173, v11, v12
	v_med3_f32 v11, v173, v10, v11
	v_med3_f32 v10, v173, v9, v10
	v_med3_f32 v9, v173, v8, v9
	v_med3_f32 v8, v173, v7, v8
	v_med3_f32 v7, v173, v6, v7
	v_med3_f32 v6, v173, v5, v6
	v_med3_f32 v5, v173, v4, v5
	v_med3_f32 v4, v173, v3, v4
	v_med3_f32 v3, v173, v2, v3
	v_max_f32_e32 v2, v173, v2
	s_waitcnt lgkmcnt(9)
	v_and_b32_e32 v174, 0xffffff80, v174
	v_or3_b32 v174, v155, v174, 44
	v_med3_f32 v17, v174, v16, v17
	v_med3_f32 v16, v174, v15, v16
	v_med3_f32 v15, v174, v14, v15
	v_med3_f32 v14, v174, v13, v14
	v_med3_f32 v13, v174, v12, v13
	v_med3_f32 v12, v174, v11, v12
	v_med3_f32 v11, v174, v10, v11
	v_med3_f32 v10, v174, v9, v10
	v_med3_f32 v9, v174, v8, v9
	v_med3_f32 v8, v174, v7, v8
	v_med3_f32 v7, v174, v6, v7
	v_med3_f32 v6, v174, v5, v6
	v_med3_f32 v5, v174, v4, v5
	v_med3_f32 v4, v174, v3, v4
	v_med3_f32 v3, v174, v2, v3
	v_max_f32_e32 v2, v174, v2
	v_and_b32_e32 v175, 0xffffff80, v175
	v_or3_b32 v175, v155, v175, 45
	v_med3_f32 v17, v175, v16, v17
	v_med3_f32 v16, v175, v15, v16
	v_med3_f32 v15, v175, v14, v15
	v_med3_f32 v14, v175, v13, v14
	v_med3_f32 v13, v175, v12, v13
	v_med3_f32 v12, v175, v11, v12
	v_med3_f32 v11, v175, v10, v11
	v_med3_f32 v10, v175, v9, v10
	v_med3_f32 v9, v175, v8, v9
	v_med3_f32 v8, v175, v7, v8
	v_med3_f32 v7, v175, v6, v7
	v_med3_f32 v6, v175, v5, v6
	v_med3_f32 v5, v175, v4, v5
	v_med3_f32 v4, v175, v3, v4
	v_med3_f32 v3, v175, v2, v3
	v_max_f32_e32 v2, v175, v2
	s_waitcnt lgkmcnt(8)
	v_and_b32_e32 v176, 0xffffff80, v176
	v_or3_b32 v176, v155, v176, 46
	v_med3_f32 v17, v176, v16, v17
	v_med3_f32 v16, v176, v15, v16
	v_med3_f32 v15, v176, v14, v15
	v_med3_f32 v14, v176, v13, v14
	v_med3_f32 v13, v176, v12, v13
	v_med3_f32 v12, v176, v11, v12
	v_med3_f32 v11, v176, v10, v11
	v_med3_f32 v10, v176, v9, v10
	v_med3_f32 v9, v176, v8, v9
	v_med3_f32 v8, v176, v7, v8
	v_med3_f32 v7, v176, v6, v7
	v_med3_f32 v6, v176, v5, v6
	v_med3_f32 v5, v176, v4, v5
	v_med3_f32 v4, v176, v3, v4
	v_med3_f32 v3, v176, v2, v3
	v_max_f32_e32 v2, v176, v2
	v_and_b32_e32 v177, 0xffffff80, v177
	v_or3_b32 v177, v155, v177, 47
	v_med3_f32 v17, v177, v16, v17
	v_med3_f32 v16, v177, v15, v16
	v_med3_f32 v15, v177, v14, v15
	v_med3_f32 v14, v177, v13, v14
	v_med3_f32 v13, v177, v12, v13
	v_med3_f32 v12, v177, v11, v12
	v_med3_f32 v11, v177, v10, v11
	v_med3_f32 v10, v177, v9, v10
	v_med3_f32 v9, v177, v8, v9
	v_med3_f32 v8, v177, v7, v8
	v_med3_f32 v7, v177, v6, v7
	v_med3_f32 v6, v177, v5, v6
	v_med3_f32 v5, v177, v4, v5
	v_med3_f32 v4, v177, v3, v4
	v_med3_f32 v3, v177, v2, v3
	v_max_f32_e32 v2, v177, v2
	s_waitcnt lgkmcnt(7)
	v_and_b32_e32 v178, 0xffffff80, v178
	v_or3_b32 v178, v155, v178, 48
	v_med3_f32 v17, v178, v16, v17
	v_med3_f32 v16, v178, v15, v16
	v_med3_f32 v15, v178, v14, v15
	v_med3_f32 v14, v178, v13, v14
	v_med3_f32 v13, v178, v12, v13
	v_med3_f32 v12, v178, v11, v12
	v_med3_f32 v11, v178, v10, v11
	v_med3_f32 v10, v178, v9, v10
	v_med3_f32 v9, v178, v8, v9
	v_med3_f32 v8, v178, v7, v8
	v_med3_f32 v7, v178, v6, v7
	v_med3_f32 v6, v178, v5, v6
	v_med3_f32 v5, v178, v4, v5
	v_med3_f32 v4, v178, v3, v4
	v_med3_f32 v3, v178, v2, v3
	v_max_f32_e32 v2, v178, v2
	v_and_b32_e32 v179, 0xffffff80, v179
	v_or3_b32 v179, v155, v179, 49
	v_med3_f32 v17, v179, v16, v17
	v_med3_f32 v16, v179, v15, v16
	v_med3_f32 v15, v179, v14, v15
	v_med3_f32 v14, v179, v13, v14
	v_med3_f32 v13, v179, v12, v13
	v_med3_f32 v12, v179, v11, v12
	v_med3_f32 v11, v179, v10, v11
	v_med3_f32 v10, v179, v9, v10
	v_med3_f32 v9, v179, v8, v9
	v_med3_f32 v8, v179, v7, v8
	v_med3_f32 v7, v179, v6, v7
	v_med3_f32 v6, v179, v5, v6
	v_med3_f32 v5, v179, v4, v5
	v_med3_f32 v4, v179, v3, v4
	v_med3_f32 v3, v179, v2, v3
	v_max_f32_e32 v2, v179, v2
	s_waitcnt lgkmcnt(6)
	v_and_b32_e32 v180, 0xffffff80, v180
	v_or3_b32 v180, v155, v180, 50
	v_med3_f32 v17, v180, v16, v17
	v_med3_f32 v16, v180, v15, v16
	v_med3_f32 v15, v180, v14, v15
	v_med3_f32 v14, v180, v13, v14
	v_med3_f32 v13, v180, v12, v13
	v_med3_f32 v12, v180, v11, v12
	v_med3_f32 v11, v180, v10, v11
	v_med3_f32 v10, v180, v9, v10
	v_med3_f32 v9, v180, v8, v9
	v_med3_f32 v8, v180, v7, v8
	v_med3_f32 v7, v180, v6, v7
	v_med3_f32 v6, v180, v5, v6
	v_med3_f32 v5, v180, v4, v5
	v_med3_f32 v4, v180, v3, v4
	v_med3_f32 v3, v180, v2, v3
	v_max_f32_e32 v2, v180, v2
	v_and_b32_e32 v181, 0xffffff80, v181
	v_or3_b32 v181, v155, v181, 51
	v_med3_f32 v17, v181, v16, v17
	v_med3_f32 v16, v181, v15, v16
	v_med3_f32 v15, v181, v14, v15
	v_med3_f32 v14, v181, v13, v14
	v_med3_f32 v13, v181, v12, v13
	v_med3_f32 v12, v181, v11, v12
	v_med3_f32 v11, v181, v10, v11
	v_med3_f32 v10, v181, v9, v10
	v_med3_f32 v9, v181, v8, v9
	v_med3_f32 v8, v181, v7, v8
	v_med3_f32 v7, v181, v6, v7
	v_med3_f32 v6, v181, v5, v6
	v_med3_f32 v5, v181, v4, v5
	v_med3_f32 v4, v181, v3, v4
	v_med3_f32 v3, v181, v2, v3
	v_max_f32_e32 v2, v181, v2
	s_waitcnt lgkmcnt(5)
	v_and_b32_e32 v182, 0xffffff80, v182
	v_or3_b32 v182, v155, v182, 52
	v_med3_f32 v17, v182, v16, v17
	v_med3_f32 v16, v182, v15, v16
	v_med3_f32 v15, v182, v14, v15
	v_med3_f32 v14, v182, v13, v14
	v_med3_f32 v13, v182, v12, v13
	v_med3_f32 v12, v182, v11, v12
	v_med3_f32 v11, v182, v10, v11
	v_med3_f32 v10, v182, v9, v10
	v_med3_f32 v9, v182, v8, v9
	v_med3_f32 v8, v182, v7, v8
	v_med3_f32 v7, v182, v6, v7
	v_med3_f32 v6, v182, v5, v6
	v_med3_f32 v5, v182, v4, v5
	v_med3_f32 v4, v182, v3, v4
	v_med3_f32 v3, v182, v2, v3
	v_max_f32_e32 v2, v182, v2
	v_and_b32_e32 v183, 0xffffff80, v183
	v_or3_b32 v183, v155, v183, 53
	v_med3_f32 v17, v183, v16, v17
	v_med3_f32 v16, v183, v15, v16
	v_med3_f32 v15, v183, v14, v15
	v_med3_f32 v14, v183, v13, v14
	v_med3_f32 v13, v183, v12, v13
	v_med3_f32 v12, v183, v11, v12
	v_med3_f32 v11, v183, v10, v11
	v_med3_f32 v10, v183, v9, v10
	v_med3_f32 v9, v183, v8, v9
	v_med3_f32 v8, v183, v7, v8
	v_med3_f32 v7, v183, v6, v7
	v_med3_f32 v6, v183, v5, v6
	v_med3_f32 v5, v183, v4, v5
	v_med3_f32 v4, v183, v3, v4
	v_med3_f32 v3, v183, v2, v3
	v_max_f32_e32 v2, v183, v2
	s_waitcnt lgkmcnt(4)
	v_and_b32_e32 v184, 0xffffff80, v184
	v_or3_b32 v184, v155, v184, 54
	v_med3_f32 v17, v184, v16, v17
	v_med3_f32 v16, v184, v15, v16
	v_med3_f32 v15, v184, v14, v15
	v_med3_f32 v14, v184, v13, v14
	v_med3_f32 v13, v184, v12, v13
	v_med3_f32 v12, v184, v11, v12
	v_med3_f32 v11, v184, v10, v11
	v_med3_f32 v10, v184, v9, v10
	v_med3_f32 v9, v184, v8, v9
	v_med3_f32 v8, v184, v7, v8
	v_med3_f32 v7, v184, v6, v7
	v_med3_f32 v6, v184, v5, v6
	v_med3_f32 v5, v184, v4, v5
	v_med3_f32 v4, v184, v3, v4
	v_med3_f32 v3, v184, v2, v3
	v_max_f32_e32 v2, v184, v2
	v_and_b32_e32 v185, 0xffffff80, v185
	v_or3_b32 v185, v155, v185, 55
	v_med3_f32 v17, v185, v16, v17
	v_med3_f32 v16, v185, v15, v16
	v_med3_f32 v15, v185, v14, v15
	v_med3_f32 v14, v185, v13, v14
	v_med3_f32 v13, v185, v12, v13
	v_med3_f32 v12, v185, v11, v12
	v_med3_f32 v11, v185, v10, v11
	v_med3_f32 v10, v185, v9, v10
	v_med3_f32 v9, v185, v8, v9
	v_med3_f32 v8, v185, v7, v8
	v_med3_f32 v7, v185, v6, v7
	v_med3_f32 v6, v185, v5, v6
	v_med3_f32 v5, v185, v4, v5
	v_med3_f32 v4, v185, v3, v4
	v_med3_f32 v3, v185, v2, v3
	v_max_f32_e32 v2, v185, v2
	s_waitcnt lgkmcnt(3)
	v_and_b32_e32 v186, 0xffffff80, v186
	v_or3_b32 v186, v155, v186, 56
	v_med3_f32 v17, v186, v16, v17
	v_med3_f32 v16, v186, v15, v16
	v_med3_f32 v15, v186, v14, v15
	v_med3_f32 v14, v186, v13, v14
	v_med3_f32 v13, v186, v12, v13
	v_med3_f32 v12, v186, v11, v12
	v_med3_f32 v11, v186, v10, v11
	v_med3_f32 v10, v186, v9, v10
	v_med3_f32 v9, v186, v8, v9
	v_med3_f32 v8, v186, v7, v8
	v_med3_f32 v7, v186, v6, v7
	v_med3_f32 v6, v186, v5, v6
	v_med3_f32 v5, v186, v4, v5
	v_med3_f32 v4, v186, v3, v4
	v_med3_f32 v3, v186, v2, v3
	v_max_f32_e32 v2, v186, v2
	v_and_b32_e32 v187, 0xffffff80, v187
	v_or3_b32 v187, v155, v187, 57
	v_med3_f32 v17, v187, v16, v17
	v_med3_f32 v16, v187, v15, v16
	v_med3_f32 v15, v187, v14, v15
	v_med3_f32 v14, v187, v13, v14
	v_med3_f32 v13, v187, v12, v13
	v_med3_f32 v12, v187, v11, v12
	v_med3_f32 v11, v187, v10, v11
	v_med3_f32 v10, v187, v9, v10
	v_med3_f32 v9, v187, v8, v9
	v_med3_f32 v8, v187, v7, v8
	v_med3_f32 v7, v187, v6, v7
	v_med3_f32 v6, v187, v5, v6
	v_med3_f32 v5, v187, v4, v5
	v_med3_f32 v4, v187, v3, v4
	v_med3_f32 v3, v187, v2, v3
	v_max_f32_e32 v2, v187, v2
	s_waitcnt lgkmcnt(2)
	v_and_b32_e32 v188, 0xffffff80, v188
	v_or3_b32 v188, v155, v188, 58
	v_med3_f32 v17, v188, v16, v17
	v_med3_f32 v16, v188, v15, v16
	v_med3_f32 v15, v188, v14, v15
	v_med3_f32 v14, v188, v13, v14
	v_med3_f32 v13, v188, v12, v13
	v_med3_f32 v12, v188, v11, v12
	v_med3_f32 v11, v188, v10, v11
	v_med3_f32 v10, v188, v9, v10
	v_med3_f32 v9, v188, v8, v9
	v_med3_f32 v8, v188, v7, v8
	v_med3_f32 v7, v188, v6, v7
	v_med3_f32 v6, v188, v5, v6
	v_med3_f32 v5, v188, v4, v5
	v_med3_f32 v4, v188, v3, v4
	v_med3_f32 v3, v188, v2, v3
	v_max_f32_e32 v2, v188, v2
	v_and_b32_e32 v189, 0xffffff80, v189
	v_or3_b32 v189, v155, v189, 59
	v_med3_f32 v17, v189, v16, v17
	v_med3_f32 v16, v189, v15, v16
	v_med3_f32 v15, v189, v14, v15
	v_med3_f32 v14, v189, v13, v14
	v_med3_f32 v13, v189, v12, v13
	v_med3_f32 v12, v189, v11, v12
	v_med3_f32 v11, v189, v10, v11
	v_med3_f32 v10, v189, v9, v10
	v_med3_f32 v9, v189, v8, v9
	v_med3_f32 v8, v189, v7, v8
	v_med3_f32 v7, v189, v6, v7
	v_med3_f32 v6, v189, v5, v6
	v_med3_f32 v5, v189, v4, v5
	v_med3_f32 v4, v189, v3, v4
	v_med3_f32 v3, v189, v2, v3
	v_max_f32_e32 v2, v189, v2
	s_waitcnt lgkmcnt(1)
	v_and_b32_e32 v190, 0xffffff80, v190
	v_or3_b32 v190, v155, v190, 60
	v_med3_f32 v17, v190, v16, v17
	v_med3_f32 v16, v190, v15, v16
	v_med3_f32 v15, v190, v14, v15
	v_med3_f32 v14, v190, v13, v14
	v_med3_f32 v13, v190, v12, v13
	v_med3_f32 v12, v190, v11, v12
	v_med3_f32 v11, v190, v10, v11
	v_med3_f32 v10, v190, v9, v10
	v_med3_f32 v9, v190, v8, v9
	v_med3_f32 v8, v190, v7, v8
	v_med3_f32 v7, v190, v6, v7
	v_med3_f32 v6, v190, v5, v6
	v_med3_f32 v5, v190, v4, v5
	v_med3_f32 v4, v190, v3, v4
	v_med3_f32 v3, v190, v2, v3
	v_max_f32_e32 v2, v190, v2
	v_and_b32_e32 v191, 0xffffff80, v191
	v_or3_b32 v191, v155, v191, 61
	v_med3_f32 v17, v191, v16, v17
	v_med3_f32 v16, v191, v15, v16
	v_med3_f32 v15, v191, v14, v15
	v_med3_f32 v14, v191, v13, v14
	v_med3_f32 v13, v191, v12, v13
	v_med3_f32 v12, v191, v11, v12
	v_med3_f32 v11, v191, v10, v11
	v_med3_f32 v10, v191, v9, v10
	v_med3_f32 v9, v191, v8, v9
	v_med3_f32 v8, v191, v7, v8
	v_med3_f32 v7, v191, v6, v7
	v_med3_f32 v6, v191, v5, v6
	v_med3_f32 v5, v191, v4, v5
	v_med3_f32 v4, v191, v3, v4
	v_med3_f32 v3, v191, v2, v3
	v_max_f32_e32 v2, v191, v2
	s_waitcnt lgkmcnt(0)
	v_and_b32_e32 v192, 0xffffff80, v192
	v_or3_b32 v192, v155, v192, 62
	v_med3_f32 v17, v192, v16, v17
	v_med3_f32 v16, v192, v15, v16
	v_med3_f32 v15, v192, v14, v15
	v_med3_f32 v14, v192, v13, v14
	v_med3_f32 v13, v192, v12, v13
	v_med3_f32 v12, v192, v11, v12
	v_med3_f32 v11, v192, v10, v11
	v_med3_f32 v10, v192, v9, v10
	v_med3_f32 v9, v192, v8, v9
	v_med3_f32 v8, v192, v7, v8
	v_med3_f32 v7, v192, v6, v7
	v_med3_f32 v6, v192, v5, v6
	v_med3_f32 v5, v192, v4, v5
	v_med3_f32 v4, v192, v3, v4
	v_med3_f32 v3, v192, v2, v3
	v_max_f32_e32 v2, v192, v2
	v_and_b32_e32 v193, 0xffffff80, v193
	v_or3_b32 v193, v155, v193, 63
	v_med3_f32 v17, v193, v16, v17
	v_med3_f32 v16, v193, v15, v16
	v_med3_f32 v15, v193, v14, v15
	v_med3_f32 v14, v193, v13, v14
	v_med3_f32 v13, v193, v12, v13
	v_med3_f32 v12, v193, v11, v12
	v_med3_f32 v11, v193, v10, v11
	v_med3_f32 v10, v193, v9, v10
	v_med3_f32 v9, v193, v8, v9
	v_med3_f32 v8, v193, v7, v8
	v_med3_f32 v7, v193, v6, v7
	v_med3_f32 v6, v193, v5, v6
	v_med3_f32 v5, v193, v4, v5
	v_med3_f32 v4, v193, v3, v4
	v_med3_f32 v3, v193, v2, v3
	v_max_f32_e32 v2, v193, v2
	s_and_saveexec_b64 s[4:5], s[40:41]
	s_cbranch_execz .LBB0_46
	ds_write_b128 v159, v[2:5]
	ds_write_b128 v159, v[6:9] offset:16
	ds_write_b128 v159, v[10:13] offset:32
	ds_write_b128 v159, v[14:17] offset:48
